# attention epilogue rows: each row waits only for its own running-output / gate row (vmcnt 15 in every row) instead of all of them at the first row
# baseline (speedup 1.0000x reference)
.LBB0_1211:
	v_readlane_b32 s4, v253, 51
	s_and_b64 vcc, exec, s[24:25]
	s_nop 0
	v_lshl_add_u32 v48, v193, 5, s4
	s_movk_i32 s4, 0x210
	v_mul_lo_u32 v49, v192, s4
	v_add_u32_e32 v57, v48, v49
	ds_read_b128 v[52:55], v57
	ds_read_b128 v[48:51], v57 offset:16
	v_readlane_b32 s4, v253, 47
	s_nop 1
	v_lshl_add_u32 v56, v192, 2, s4
	s_cbranch_vccz .LBB0_1213
	ds_read_b32 v58, v56
	s_waitcnt vmcnt(15)
	v_lshlrev_b32_e32 v60, 16, v84
	v_and_b32_e32 v61, 0xffff0000, v84
	s_waitcnt lgkmcnt(0)
	v_pk_fma_f32 v[52:53], v[58:59], v[60:61], v[52:53] op_sel_hi:[0,1,1]
	v_lshlrev_b32_e32 v60, 16, v85
	v_and_b32_e32 v61, 0xffff0000, v85
	v_pk_fma_f32 v[54:55], v[58:59], v[60:61], v[54:55] op_sel_hi:[0,1,1]
	v_lshlrev_b32_e32 v60, 16, v86
	v_and_b32_e32 v61, 0xffff0000, v86
	v_pk_fma_f32 v[48:49], v[58:59], v[60:61], v[48:49] op_sel_hi:[0,1,1]
	v_lshlrev_b32_e32 v60, 16, v87
	v_and_b32_e32 v61, 0xffff0000, v87
	v_pk_fma_f32 v[50:51], v[58:59], v[60:61], v[50:51] op_sel_hi:[0,1,1]
.LBB0_1213:
	s_and_b64 vcc, exec, s[46:47]
	s_cbranch_vccnz .LBB0_1215
	s_waitcnt vmcnt(15)
	v_lshlrev_b32_e32 v86, 16, v126
	v_and_b32_e32 v87, 0xffff0000, v126
	v_lshlrev_b32_e32 v126, 16, v127
	v_lshlrev_b32_e32 v58, 16, v124
	v_and_b32_e32 v59, 0xffff0000, v124
	v_lshlrev_b32_e32 v62, 16, v125
	v_and_b32_e32 v63, 0xffff0000, v125
	v_and_b32_e32 v127, 0xffff0000, v127
	v_mul_f32_e32 v138, 0xbfb8aa3b, v126
	v_mul_f32_e32 v60, 0xbfb8aa3b, v58
	v_mul_f32_e32 v61, 0xbfb8aa3b, v59
	v_mul_f32_e32 v84, 0xbfb8aa3b, v62
	v_mul_f32_e32 v85, 0xbfb8aa3b, v63
	v_mul_f32_e32 v124, 0xbfb8aa3b, v86
	v_mul_f32_e32 v125, 0xbfb8aa3b, v87
	v_exp_f32_e32 v138, v138
	v_mul_f32_e32 v140, 0xbfb8aa3b, v127
	v_exp_f32_e32 v60, v60
	v_exp_f32_e32 v61, v61
	v_exp_f32_e32 v84, v84
	v_exp_f32_e32 v85, v85
	v_exp_f32_e32 v124, v124
	v_exp_f32_e32 v125, v125
	v_exp_f32_e32 v140, v140
	v_add_f32_e32 v138, 1.0, v138
	v_add_f32_e32 v60, 1.0, v60
	v_add_f32_e32 v61, 1.0, v61
	v_add_f32_e32 v84, 1.0, v84
	v_add_f32_e32 v85, 1.0, v85
	v_add_f32_e32 v124, 1.0, v124
	v_add_f32_e32 v125, 1.0, v125
	v_rcp_f32_e32 v144, v138
	v_add_f32_e32 v138, 1.0, v140
	v_rcp_f32_e32 v60, v60
	v_rcp_f32_e32 v61, v61
	v_rcp_f32_e32 v84, v84
	v_rcp_f32_e32 v85, v85
	v_rcp_f32_e32 v124, v124
	v_rcp_f32_e32 v125, v125
	v_rcp_f32_e32 v145, v138
	v_pk_mul_f32 v[58:59], v[60:61], v[58:59]
	v_pk_mul_f32 v[60:61], v[84:85], v[62:63]
	v_pk_mul_f32 v[62:63], v[124:125], v[86:87]
	v_pk_mul_f32 v[84:85], v[144:145], v[126:127]
	s_waitcnt lgkmcnt(1)
	v_pk_mul_f32 v[54:55], v[54:55], v[60:61]
	s_waitcnt lgkmcnt(0)
	v_pk_mul_f32 v[50:51], v[50:51], v[84:85]
	v_pk_mul_f32 v[48:49], v[48:49], v[62:63]
	v_pk_mul_f32 v[52:53], v[52:53], v[58:59]
.LBB0_1215:
	s_waitcnt lgkmcnt(1)
	v_cvt_pk_bf16_f32 v52, v52, v53
	v_cvt_pk_bf16_f32 v53, v54, v55
	s_waitcnt lgkmcnt(0)
	v_cvt_pk_bf16_f32 v54, v48, v49
	v_cvt_pk_bf16_f32 v55, v50, v51
	global_store_dwordx4 v[142:143], v[52:55], off sc1
	ds_read_b128 v[52:55], v57 offset:2112
	ds_read_b128 v[48:51], v57 offset:2128
	s_and_b64 vcc, exec, s[44:45]
	s_cbranch_vccnz .LBB0_1217
	ds_read_b32 v58, v56 offset:16
	s_waitcnt vmcnt(15)
	v_lshlrev_b32_e32 v60, 16, v96
	v_and_b32_e32 v61, 0xffff0000, v96
	s_waitcnt lgkmcnt(0)
	v_pk_fma_f32 v[52:53], v[58:59], v[60:61], v[52:53] op_sel_hi:[0,1,1]
	v_lshlrev_b32_e32 v60, 16, v97
	v_and_b32_e32 v61, 0xffff0000, v97
	v_pk_fma_f32 v[54:55], v[58:59], v[60:61], v[54:55] op_sel_hi:[0,1,1]
	v_lshlrev_b32_e32 v60, 16, v98
	v_and_b32_e32 v61, 0xffff0000, v98
	v_pk_fma_f32 v[48:49], v[58:59], v[60:61], v[48:49] op_sel_hi:[0,1,1]
	v_lshlrev_b32_e32 v60, 16, v99
	v_and_b32_e32 v61, 0xffff0000, v99
	v_pk_fma_f32 v[50:51], v[58:59], v[60:61], v[50:51] op_sel_hi:[0,1,1]
.LBB0_1217:
	s_and_b64 vcc, exec, s[46:47]
	s_cbranch_vccnz .LBB0_1219
	s_waitcnt vmcnt(15)
	v_lshlrev_b32_e32 v58, 16, v120
	v_and_b32_e32 v59, 0xffff0000, v120
	v_lshlrev_b32_e32 v62, 16, v121
	v_and_b32_e32 v63, 0xffff0000, v121
	v_lshlrev_b32_e32 v86, 16, v122
	v_and_b32_e32 v87, 0xffff0000, v122
	v_lshlrev_b32_e32 v98, 16, v123
	v_and_b32_e32 v99, 0xffff0000, v123
	v_mul_f32_e32 v60, 0xbfb8aa3b, v58
	v_mul_f32_e32 v61, 0xbfb8aa3b, v59
	v_mul_f32_e32 v84, 0xbfb8aa3b, v62
	v_mul_f32_e32 v85, 0xbfb8aa3b, v63
	v_mul_f32_e32 v96, 0xbfb8aa3b, v86
	v_mul_f32_e32 v97, 0xbfb8aa3b, v87
	v_mul_f32_e32 v120, 0xbfb8aa3b, v98
	v_mul_f32_e32 v121, 0xbfb8aa3b, v99
	v_exp_f32_e32 v60, v60
	v_exp_f32_e32 v61, v61
	v_exp_f32_e32 v84, v84
	v_exp_f32_e32 v85, v85
	v_exp_f32_e32 v96, v96
	v_exp_f32_e32 v97, v97
	v_exp_f32_e32 v120, v120
	v_exp_f32_e32 v121, v121
	v_add_f32_e32 v60, 1.0, v60
	v_add_f32_e32 v61, 1.0, v61
	v_add_f32_e32 v84, 1.0, v84
	v_add_f32_e32 v85, 1.0, v85
	v_add_f32_e32 v96, 1.0, v96
	v_add_f32_e32 v97, 1.0, v97
	v_add_f32_e32 v120, 1.0, v120
	v_add_f32_e32 v121, 1.0, v121
	v_rcp_f32_e32 v60, v60
	v_rcp_f32_e32 v61, v61
	v_rcp_f32_e32 v84, v84
	v_rcp_f32_e32 v85, v85
	v_rcp_f32_e32 v96, v96
	v_rcp_f32_e32 v97, v97
	v_rcp_f32_e32 v120, v120
	v_rcp_f32_e32 v121, v121
	v_pk_mul_f32 v[58:59], v[60:61], v[58:59]
	v_pk_mul_f32 v[60:61], v[84:85], v[62:63]
	v_pk_mul_f32 v[62:63], v[96:97], v[86:87]
	v_pk_mul_f32 v[84:85], v[120:121], v[98:99]
	s_waitcnt lgkmcnt(1)
	v_pk_mul_f32 v[54:55], v[54:55], v[60:61]
	s_waitcnt lgkmcnt(0)
	v_pk_mul_f32 v[50:51], v[50:51], v[84:85]
	v_pk_mul_f32 v[48:49], v[48:49], v[62:63]
	v_pk_mul_f32 v[52:53], v[52:53], v[58:59]
.LBB0_1219:
	s_waitcnt lgkmcnt(1)
	v_cvt_pk_bf16_f32 v52, v52, v53
	v_cvt_pk_bf16_f32 v53, v54, v55
	s_waitcnt lgkmcnt(0)
	v_cvt_pk_bf16_f32 v54, v48, v49
	v_cvt_pk_bf16_f32 v55, v50, v51
	v_lshl_add_u64 v[48:49], s[0:1], 1, v[142:143]
	global_store_dwordx4 v[48:49], v[52:55], off sc1
	ds_read_b128 v[52:55], v57 offset:4224
	ds_read_b128 v[48:51], v57 offset:4240
	s_and_b64 vcc, exec, s[44:45]
	s_cbranch_vccnz .LBB0_1221
	ds_read_b32 v58, v56 offset:32
	s_waitcnt vmcnt(15)
	v_lshlrev_b32_e32 v60, 16, v88
	v_and_b32_e32 v61, 0xffff0000, v88
	s_waitcnt lgkmcnt(0)
	v_pk_fma_f32 v[52:53], v[58:59], v[60:61], v[52:53] op_sel_hi:[0,1,1]
	v_lshlrev_b32_e32 v60, 16, v89
	v_and_b32_e32 v61, 0xffff0000, v89
	v_pk_fma_f32 v[54:55], v[58:59], v[60:61], v[54:55] op_sel_hi:[0,1,1]
	v_lshlrev_b32_e32 v60, 16, v90
	v_and_b32_e32 v61, 0xffff0000, v90
	v_pk_fma_f32 v[48:49], v[58:59], v[60:61], v[48:49] op_sel_hi:[0,1,1]
	v_lshlrev_b32_e32 v60, 16, v91
	v_and_b32_e32 v61, 0xffff0000, v91
	v_pk_fma_f32 v[50:51], v[58:59], v[60:61], v[50:51] op_sel_hi:[0,1,1]
.LBB0_1221:
	s_and_b64 vcc, exec, s[46:47]
	s_cbranch_vccnz .LBB0_1223
	s_waitcnt vmcnt(15)
	v_lshlrev_b32_e32 v58, 16, v116
	v_and_b32_e32 v59, 0xffff0000, v116
	v_lshlrev_b32_e32 v62, 16, v117
	v_and_b32_e32 v63, 0xffff0000, v117
	v_lshlrev_b32_e32 v86, 16, v118
	v_and_b32_e32 v87, 0xffff0000, v118
	v_lshlrev_b32_e32 v90, 16, v119
	v_and_b32_e32 v91, 0xffff0000, v119
	v_mul_f32_e32 v60, 0xbfb8aa3b, v58
	v_mul_f32_e32 v61, 0xbfb8aa3b, v59
	v_mul_f32_e32 v84, 0xbfb8aa3b, v62
	v_mul_f32_e32 v85, 0xbfb8aa3b, v63
	v_mul_f32_e32 v88, 0xbfb8aa3b, v86
	v_mul_f32_e32 v89, 0xbfb8aa3b, v87
	v_mul_f32_e32 v96, 0xbfb8aa3b, v90
	v_mul_f32_e32 v97, 0xbfb8aa3b, v91
	v_exp_f32_e32 v60, v60
	v_exp_f32_e32 v61, v61
	v_exp_f32_e32 v84, v84
	v_exp_f32_e32 v85, v85
	v_exp_f32_e32 v88, v88
	v_exp_f32_e32 v89, v89
	v_exp_f32_e32 v96, v96
	v_exp_f32_e32 v97, v97
	v_add_f32_e32 v60, 1.0, v60
	v_add_f32_e32 v61, 1.0, v61
	v_add_f32_e32 v84, 1.0, v84
	v_add_f32_e32 v85, 1.0, v85
	v_add_f32_e32 v88, 1.0, v88
	v_add_f32_e32 v89, 1.0, v89
	v_add_f32_e32 v96, 1.0, v96
	v_add_f32_e32 v97, 1.0, v97
	v_rcp_f32_e32 v60, v60
	v_rcp_f32_e32 v61, v61
	v_rcp_f32_e32 v84, v84
	v_rcp_f32_e32 v85, v85
	v_rcp_f32_e32 v88, v88
	v_rcp_f32_e32 v89, v89
	v_rcp_f32_e32 v96, v96
	v_rcp_f32_e32 v97, v97
	v_pk_mul_f32 v[58:59], v[60:61], v[58:59]
	v_pk_mul_f32 v[60:61], v[84:85], v[62:63]
	v_pk_mul_f32 v[62:63], v[88:89], v[86:87]
	v_pk_mul_f32 v[84:85], v[96:97], v[90:91]
	s_waitcnt lgkmcnt(1)
	v_pk_mul_f32 v[54:55], v[54:55], v[60:61]
	s_waitcnt lgkmcnt(0)
	v_pk_mul_f32 v[50:51], v[50:51], v[84:85]
	v_pk_mul_f32 v[48:49], v[48:49], v[62:63]
	v_pk_mul_f32 v[52:53], v[52:53], v[58:59]
.LBB0_1223:
	s_waitcnt lgkmcnt(1)
	v_cvt_pk_bf16_f32 v52, v52, v53
	v_cvt_pk_bf16_f32 v53, v54, v55
	s_waitcnt lgkmcnt(0)
	v_cvt_pk_bf16_f32 v54, v48, v49
	v_cvt_pk_bf16_f32 v55, v50, v51
	v_lshl_add_u64 v[48:49], s[82:83], 1, v[142:143]
	global_store_dwordx4 v[48:49], v[52:55], off sc1
	ds_read_b128 v[52:55], v57 offset:6336
	ds_read_b128 v[48:51], v57 offset:6352
	s_and_b64 vcc, exec, s[44:45]
	s_cbranch_vccnz .LBB0_1225
	ds_read_b32 v58, v56 offset:48
	s_waitcnt vmcnt(15)
	v_lshlrev_b32_e32 v60, 16, v80
	v_and_b32_e32 v61, 0xffff0000, v80
	s_waitcnt lgkmcnt(0)
	v_pk_fma_f32 v[52:53], v[58:59], v[60:61], v[52:53] op_sel_hi:[0,1,1]
	v_lshlrev_b32_e32 v60, 16, v81
	v_and_b32_e32 v61, 0xffff0000, v81
	v_pk_fma_f32 v[54:55], v[58:59], v[60:61], v[54:55] op_sel_hi:[0,1,1]
	v_lshlrev_b32_e32 v60, 16, v82
	v_and_b32_e32 v61, 0xffff0000, v82
	v_pk_fma_f32 v[48:49], v[58:59], v[60:61], v[48:49] op_sel_hi:[0,1,1]
	v_lshlrev_b32_e32 v60, 16, v83
	v_and_b32_e32 v61, 0xffff0000, v83
	v_pk_fma_f32 v[50:51], v[58:59], v[60:61], v[50:51] op_sel_hi:[0,1,1]
.LBB0_1225:
	s_and_b64 vcc, exec, s[46:47]
	s_cbranch_vccnz .LBB0_1227
	s_waitcnt vmcnt(15)
	v_lshlrev_b32_e32 v58, 16, v112
	v_and_b32_e32 v59, 0xffff0000, v112
	v_lshlrev_b32_e32 v62, 16, v113
	v_and_b32_e32 v63, 0xffff0000, v113
	v_lshlrev_b32_e32 v82, 16, v114
	v_and_b32_e32 v83, 0xffff0000, v114
	v_lshlrev_b32_e32 v86, 16, v115
	v_and_b32_e32 v87, 0xffff0000, v115
	v_mul_f32_e32 v60, 0xbfb8aa3b, v58
	v_mul_f32_e32 v61, 0xbfb8aa3b, v59
	v_mul_f32_e32 v80, 0xbfb8aa3b, v62
	v_mul_f32_e32 v81, 0xbfb8aa3b, v63
	v_mul_f32_e32 v84, 0xbfb8aa3b, v82
	v_mul_f32_e32 v85, 0xbfb8aa3b, v83
	v_mul_f32_e32 v88, 0xbfb8aa3b, v86
	v_mul_f32_e32 v89, 0xbfb8aa3b, v87
	v_exp_f32_e32 v60, v60
	v_exp_f32_e32 v61, v61
	v_exp_f32_e32 v80, v80
	v_exp_f32_e32 v81, v81
	v_exp_f32_e32 v84, v84
	v_exp_f32_e32 v85, v85
	v_exp_f32_e32 v88, v88
	v_exp_f32_e32 v89, v89
	v_add_f32_e32 v60, 1.0, v60
	v_add_f32_e32 v61, 1.0, v61
	v_add_f32_e32 v80, 1.0, v80
	v_add_f32_e32 v81, 1.0, v81
	v_add_f32_e32 v84, 1.0, v84
	v_add_f32_e32 v85, 1.0, v85
	v_add_f32_e32 v88, 1.0, v88
	v_add_f32_e32 v89, 1.0, v89
	v_rcp_f32_e32 v60, v60
	v_rcp_f32_e32 v61, v61
	v_rcp_f32_e32 v80, v80
	v_rcp_f32_e32 v81, v81
	v_rcp_f32_e32 v84, v84
	v_rcp_f32_e32 v85, v85
	v_rcp_f32_e32 v88, v88
	v_rcp_f32_e32 v89, v89
	v_pk_mul_f32 v[58:59], v[60:61], v[58:59]
	v_pk_mul_f32 v[60:61], v[80:81], v[62:63]
	v_pk_mul_f32 v[62:63], v[84:85], v[82:83]
	v_pk_mul_f32 v[80:81], v[88:89], v[86:87]
	s_waitcnt lgkmcnt(1)
	v_pk_mul_f32 v[54:55], v[54:55], v[60:61]
	s_waitcnt lgkmcnt(0)
	v_pk_mul_f32 v[50:51], v[50:51], v[80:81]
	v_pk_mul_f32 v[48:49], v[48:49], v[62:63]
	v_pk_mul_f32 v[52:53], v[52:53], v[58:59]
.LBB0_1227:
	s_waitcnt lgkmcnt(1)
	v_cvt_pk_bf16_f32 v52, v52, v53
	v_cvt_pk_bf16_f32 v53, v54, v55
	s_waitcnt lgkmcnt(0)
	v_cvt_pk_bf16_f32 v54, v48, v49
	v_cvt_pk_bf16_f32 v55, v50, v51
	v_lshl_add_u64 v[48:49], s[84:85], 1, v[142:143]
	global_store_dwordx4 v[48:49], v[52:55], off sc1
	ds_read_b128 v[52:55], v57 offset:8448
	ds_read_b128 v[48:51], v57 offset:8464
	s_and_b64 vcc, exec, s[44:45]
	s_cbranch_vccnz .LBB0_1229
	ds_read_b32 v58, v56 offset:64
	s_waitcnt vmcnt(15)
	v_lshlrev_b32_e32 v60, 16, v76
	v_and_b32_e32 v61, 0xffff0000, v76
	s_waitcnt lgkmcnt(0)
	v_pk_fma_f32 v[52:53], v[58:59], v[60:61], v[52:53] op_sel_hi:[0,1,1]
	v_lshlrev_b32_e32 v60, 16, v77
	v_and_b32_e32 v61, 0xffff0000, v77
	v_pk_fma_f32 v[54:55], v[58:59], v[60:61], v[54:55] op_sel_hi:[0,1,1]
	v_lshlrev_b32_e32 v60, 16, v78
	v_and_b32_e32 v61, 0xffff0000, v78
	v_pk_fma_f32 v[48:49], v[58:59], v[60:61], v[48:49] op_sel_hi:[0,1,1]
	v_lshlrev_b32_e32 v60, 16, v79
	v_and_b32_e32 v61, 0xffff0000, v79
	v_pk_fma_f32 v[50:51], v[58:59], v[60:61], v[50:51] op_sel_hi:[0,1,1]
.LBB0_1229:
	s_and_b64 vcc, exec, s[46:47]
	s_cbranch_vccnz .LBB0_1231
	s_waitcnt vmcnt(15)
	v_lshlrev_b32_e32 v58, 16, v108
	v_and_b32_e32 v59, 0xffff0000, v108
	v_lshlrev_b32_e32 v62, 16, v109
	v_and_b32_e32 v63, 0xffff0000, v109
	v_lshlrev_b32_e32 v78, 16, v110
	v_and_b32_e32 v79, 0xffff0000, v110
	v_lshlrev_b32_e32 v82, 16, v111
	v_and_b32_e32 v83, 0xffff0000, v111
	v_mul_f32_e32 v60, 0xbfb8aa3b, v58
	v_mul_f32_e32 v61, 0xbfb8aa3b, v59
	v_mul_f32_e32 v76, 0xbfb8aa3b, v62
	v_mul_f32_e32 v77, 0xbfb8aa3b, v63
	v_mul_f32_e32 v80, 0xbfb8aa3b, v78
	v_mul_f32_e32 v81, 0xbfb8aa3b, v79
	v_mul_f32_e32 v84, 0xbfb8aa3b, v82
	v_mul_f32_e32 v85, 0xbfb8aa3b, v83
	v_exp_f32_e32 v60, v60
	v_exp_f32_e32 v61, v61
	v_exp_f32_e32 v76, v76
	v_exp_f32_e32 v77, v77
	v_exp_f32_e32 v80, v80
	v_exp_f32_e32 v81, v81
	v_exp_f32_e32 v84, v84
	v_exp_f32_e32 v85, v85
	v_add_f32_e32 v60, 1.0, v60
	v_add_f32_e32 v61, 1.0, v61
	v_add_f32_e32 v76, 1.0, v76
	v_add_f32_e32 v77, 1.0, v77
	v_add_f32_e32 v80, 1.0, v80
	v_add_f32_e32 v81, 1.0, v81
	v_add_f32_e32 v84, 1.0, v84
	v_add_f32_e32 v85, 1.0, v85
	v_rcp_f32_e32 v60, v60
	v_rcp_f32_e32 v61, v61
	v_rcp_f32_e32 v76, v76
	v_rcp_f32_e32 v77, v77
	v_rcp_f32_e32 v80, v80
	v_rcp_f32_e32 v81, v81
	v_rcp_f32_e32 v84, v84
	v_rcp_f32_e32 v85, v85
	v_pk_mul_f32 v[58:59], v[60:61], v[58:59]
	v_pk_mul_f32 v[60:61], v[76:77], v[62:63]
	v_pk_mul_f32 v[62:63], v[80:81], v[78:79]
	v_pk_mul_f32 v[76:77], v[84:85], v[82:83]
	s_waitcnt lgkmcnt(1)
	v_pk_mul_f32 v[54:55], v[54:55], v[60:61]
	s_waitcnt lgkmcnt(0)
	v_pk_mul_f32 v[50:51], v[50:51], v[76:77]
	v_pk_mul_f32 v[48:49], v[48:49], v[62:63]
	v_pk_mul_f32 v[52:53], v[52:53], v[58:59]
.LBB0_1231:
	s_waitcnt lgkmcnt(1)
	v_cvt_pk_bf16_f32 v52, v52, v53
	v_cvt_pk_bf16_f32 v53, v54, v55
	s_waitcnt lgkmcnt(0)
	v_cvt_pk_bf16_f32 v54, v48, v49
	v_cvt_pk_bf16_f32 v55, v50, v51
	v_lshl_add_u64 v[48:49], s[86:87], 1, v[142:143]
	global_store_dwordx4 v[48:49], v[52:55], off sc1
	ds_read_b128 v[52:55], v57 offset:10560
	ds_read_b128 v[48:51], v57 offset:10576
	s_and_b64 vcc, exec, s[44:45]
	s_cbranch_vccnz .LBB0_1233
	ds_read_b32 v58, v56 offset:80
	s_waitcnt vmcnt(15)
	v_lshlrev_b32_e32 v60, 16, v72
	v_and_b32_e32 v61, 0xffff0000, v72
	s_waitcnt lgkmcnt(0)
	v_pk_fma_f32 v[52:53], v[58:59], v[60:61], v[52:53] op_sel_hi:[0,1,1]
	v_lshlrev_b32_e32 v60, 16, v73
	v_and_b32_e32 v61, 0xffff0000, v73
	v_pk_fma_f32 v[54:55], v[58:59], v[60:61], v[54:55] op_sel_hi:[0,1,1]
	v_lshlrev_b32_e32 v60, 16, v74
	v_and_b32_e32 v61, 0xffff0000, v74
	v_pk_fma_f32 v[48:49], v[58:59], v[60:61], v[48:49] op_sel_hi:[0,1,1]
	v_lshlrev_b32_e32 v60, 16, v75
	v_and_b32_e32 v61, 0xffff0000, v75
	v_pk_fma_f32 v[50:51], v[58:59], v[60:61], v[50:51] op_sel_hi:[0,1,1]
.LBB0_1233:
	s_and_b64 vcc, exec, s[46:47]
	s_cbranch_vccnz .LBB0_1235
	s_waitcnt vmcnt(15)
	v_lshlrev_b32_e32 v58, 16, v104
	v_and_b32_e32 v59, 0xffff0000, v104
	v_lshlrev_b32_e32 v62, 16, v105
	v_and_b32_e32 v63, 0xffff0000, v105
	v_lshlrev_b32_e32 v74, 16, v106
	v_and_b32_e32 v75, 0xffff0000, v106
	v_lshlrev_b32_e32 v78, 16, v107
	v_and_b32_e32 v79, 0xffff0000, v107
	v_mul_f32_e32 v60, 0xbfb8aa3b, v58
	v_mul_f32_e32 v61, 0xbfb8aa3b, v59
	v_mul_f32_e32 v72, 0xbfb8aa3b, v62
	v_mul_f32_e32 v73, 0xbfb8aa3b, v63
	v_mul_f32_e32 v76, 0xbfb8aa3b, v74
	v_mul_f32_e32 v77, 0xbfb8aa3b, v75
	v_mul_f32_e32 v80, 0xbfb8aa3b, v78
	v_mul_f32_e32 v81, 0xbfb8aa3b, v79
	v_exp_f32_e32 v60, v60
	v_exp_f32_e32 v61, v61
	v_exp_f32_e32 v72, v72
	v_exp_f32_e32 v73, v73
	v_exp_f32_e32 v76, v76
	v_exp_f32_e32 v77, v77
	v_exp_f32_e32 v80, v80
	v_exp_f32_e32 v81, v81
	v_add_f32_e32 v60, 1.0, v60
	v_add_f32_e32 v61, 1.0, v61
	v_add_f32_e32 v72, 1.0, v72
	v_add_f32_e32 v73, 1.0, v73
	v_add_f32_e32 v76, 1.0, v76
	v_add_f32_e32 v77, 1.0, v77
	v_add_f32_e32 v80, 1.0, v80
	v_add_f32_e32 v81, 1.0, v81
	v_rcp_f32_e32 v60, v60
	v_rcp_f32_e32 v61, v61
	v_rcp_f32_e32 v72, v72
	v_rcp_f32_e32 v73, v73
	v_rcp_f32_e32 v76, v76
	v_rcp_f32_e32 v77, v77
	v_rcp_f32_e32 v80, v80
	v_rcp_f32_e32 v81, v81
	v_pk_mul_f32 v[58:59], v[60:61], v[58:59]
	v_pk_mul_f32 v[60:61], v[72:73], v[62:63]
	v_pk_mul_f32 v[62:63], v[76:77], v[74:75]
	v_pk_mul_f32 v[72:73], v[80:81], v[78:79]
	s_waitcnt lgkmcnt(1)
	v_pk_mul_f32 v[54:55], v[54:55], v[60:61]
	s_waitcnt lgkmcnt(0)
	v_pk_mul_f32 v[50:51], v[50:51], v[72:73]
	v_pk_mul_f32 v[48:49], v[48:49], v[62:63]
	v_pk_mul_f32 v[52:53], v[52:53], v[58:59]
.LBB0_1235:
	s_waitcnt lgkmcnt(1)
	v_cvt_pk_bf16_f32 v52, v52, v53
	v_cvt_pk_bf16_f32 v53, v54, v55
	s_waitcnt lgkmcnt(0)
	v_cvt_pk_bf16_f32 v54, v48, v49
	v_cvt_pk_bf16_f32 v55, v50, v51
	v_lshl_add_u64 v[48:49], s[88:89], 1, v[142:143]
	global_store_dwordx4 v[48:49], v[52:55], off sc1
	ds_read_b128 v[52:55], v57 offset:12672
	ds_read_b128 v[48:51], v57 offset:12688
	s_and_b64 vcc, exec, s[44:45]
	s_cbranch_vccnz .LBB0_1237
	ds_read_b32 v58, v56 offset:96
	s_waitcnt vmcnt(15)
	v_lshlrev_b32_e32 v60, 16, v68
	v_and_b32_e32 v61, 0xffff0000, v68
	s_waitcnt lgkmcnt(0)
	v_pk_fma_f32 v[52:53], v[58:59], v[60:61], v[52:53] op_sel_hi:[0,1,1]
	v_lshlrev_b32_e32 v60, 16, v69
	v_and_b32_e32 v61, 0xffff0000, v69
	v_pk_fma_f32 v[54:55], v[58:59], v[60:61], v[54:55] op_sel_hi:[0,1,1]
	v_lshlrev_b32_e32 v60, 16, v70
	v_and_b32_e32 v61, 0xffff0000, v70
	v_pk_fma_f32 v[48:49], v[58:59], v[60:61], v[48:49] op_sel_hi:[0,1,1]
	v_lshlrev_b32_e32 v60, 16, v71
	v_and_b32_e32 v61, 0xffff0000, v71
	v_pk_fma_f32 v[50:51], v[58:59], v[60:61], v[50:51] op_sel_hi:[0,1,1]
.LBB0_1237:
	s_and_b64 vcc, exec, s[46:47]
	s_cbranch_vccnz .LBB0_1239
	s_waitcnt vmcnt(15)
	v_lshlrev_b32_e32 v58, 16, v100
	v_and_b32_e32 v59, 0xffff0000, v100
	v_lshlrev_b32_e32 v62, 16, v101
	v_and_b32_e32 v63, 0xffff0000, v101
	v_lshlrev_b32_e32 v70, 16, v102
	v_and_b32_e32 v71, 0xffff0000, v102
	v_lshlrev_b32_e32 v74, 16, v103
	v_and_b32_e32 v75, 0xffff0000, v103
	v_mul_f32_e32 v60, 0xbfb8aa3b, v58
	v_mul_f32_e32 v61, 0xbfb8aa3b, v59
	v_mul_f32_e32 v68, 0xbfb8aa3b, v62
	v_mul_f32_e32 v69, 0xbfb8aa3b, v63
	v_mul_f32_e32 v72, 0xbfb8aa3b, v70
	v_mul_f32_e32 v73, 0xbfb8aa3b, v71
	v_mul_f32_e32 v76, 0xbfb8aa3b, v74
	v_mul_f32_e32 v77, 0xbfb8aa3b, v75
	v_exp_f32_e32 v60, v60
	v_exp_f32_e32 v61, v61
	v_exp_f32_e32 v68, v68
	v_exp_f32_e32 v69, v69
	v_exp_f32_e32 v72, v72
	v_exp_f32_e32 v73, v73
	v_exp_f32_e32 v76, v76
	v_exp_f32_e32 v77, v77
	v_add_f32_e32 v60, 1.0, v60
	v_add_f32_e32 v61, 1.0, v61
	v_add_f32_e32 v68, 1.0, v68
	v_add_f32_e32 v69, 1.0, v69
	v_add_f32_e32 v72, 1.0, v72
	v_add_f32_e32 v73, 1.0, v73
	v_add_f32_e32 v76, 1.0, v76
	v_add_f32_e32 v77, 1.0, v77
	v_rcp_f32_e32 v60, v60
	v_rcp_f32_e32 v61, v61
	v_rcp_f32_e32 v68, v68
	v_rcp_f32_e32 v69, v69
	v_rcp_f32_e32 v72, v72
	v_rcp_f32_e32 v73, v73
	v_rcp_f32_e32 v76, v76
	v_rcp_f32_e32 v77, v77
	v_pk_mul_f32 v[58:59], v[60:61], v[58:59]
	v_pk_mul_f32 v[60:61], v[68:69], v[62:63]
	v_pk_mul_f32 v[62:63], v[72:73], v[70:71]
	v_pk_mul_f32 v[68:69], v[76:77], v[74:75]
	s_waitcnt lgkmcnt(1)
	v_pk_mul_f32 v[54:55], v[54:55], v[60:61]
	s_waitcnt lgkmcnt(0)
	v_pk_mul_f32 v[50:51], v[50:51], v[68:69]
	v_pk_mul_f32 v[48:49], v[48:49], v[62:63]
	v_pk_mul_f32 v[52:53], v[52:53], v[58:59]
